# norm2 row loop (P6): ln2 gain vector loaded once before the loop instead of 8 serialized loads+waits per row; counted vmcnt so next row's loads stay in flight during the row's reduce/scale/store
# speedup vs baseline: 1.0103x; 1.0059x over previous
; __device__ __forceinline__ unsigned cvtpk(float lo, float hi) { return pg8::cvt_pk_bf16(lo, hi); }
; __device__ __forceinline__ void rms_load(const float* xrow, int lane, f32x4 (&v)[8]) {
;     const f32x4* xr = (const f32x4*)xrow + lane;
; #pragma unroll
;     for (int j = 0; j < 8; ++j) v[j] = xr[64 * j];
; }
; __device__ __forceinline__ float rms_rstd(const f32x4 (&v)[8]) {
;     float s = 0.f;
; #pragma unroll
;     for (int j = 0; j < 8; ++j) s += (v[j].x * v[j].x + v[j].y * v[j].y) + (v[j].z * v[j].z + v[j].w * v[j].w);
;     return 1.0f / sqrtf(wave_sum(s) * (1.f / DM) + EPS);
; }
; __device__ __forceinline__ void rms_store_bf16(const f32x4 (&v)[8], const float* g, bf16* orow, int lane) {
;     const float rstd = rms_rstd(v); const f32x4* gr = (const f32x4*)g + lane; v2u* o8 = (v2u*)orow + lane;
; #pragma unroll
;     for (int j = 0; j < 8; ++j) { const f32x4 gg = gr[64 * j]; v2u w; w.x = cvtpk(v[j].x * rstd * gg.x, v[j].y * rstd * gg.y); w.y = cvtpk(v[j].z * rstd * gg.z, v[j].w * rstd * gg.w); o8[64 * j] = w; }
; }
; __global__ void __launch_bounds__(512, 2) fwd_megakernel(Args args) {
;     ...
;     if (IN(6)) { int t_b = threadIdx.x; asm volatile("" : "+v"(t_b)); const int lane = t_b & 63; int m = gw; f32x4 cur[8]; if (m < NTOK) rms_load(args.out + (size_t)m * DM, lane, cur);
;         for (; m < NTOK; m += NGW) { const int mn = m + NGW; f32x4 nxt[8]; if (mn < NTOK) rms_load(args.out + (size_t)mn * DM, lane, nxt);
;             rms_store_bf16(cur, args.in[10], XN + (size_t)m * DM, lane);
; #pragma unroll
;             for (int j = 0; j < 8; ++j) cur[j] = nxt[j]; } }
.LBB0_620:
	s_cmp_lt_i32 s58, 7
	s_cselect_b64 s[0:1], -1, 0
	s_and_b64 s[0:1], s[0:1], s[4:5]
	s_andn2_b64 vcc, exec, s[0:1]
	s_cbranch_vccnz .LBB0_626
	v_mov_b32_e32 v0, v252
	s_cmpk_gt_i32 s70, 0x5fff
	s_cbranch_scc1 .LBB0_626
	s_ashr_i32 s71, s70, 31
	s_lshl_b64 s[4:5], s[70:71], 13
	v_and_b32_e32 v8, 63, v0
	s_add_u32 s4, s48, s4
	s_addc_u32 s5, s49, s5
	v_lshlrev_b32_e32 v4, 4, v8
	v_mov_b32_e32 v5, 0
	v_lshl_add_u64 v[0:1], s[4:5], 0, v[4:5]
	s_movk_i32 s3, 0x1000
	v_add_co_u32_e32 v6, vcc, s3, v0
	global_load_dwordx4 v[60:63], v4, s[4:5]
	global_load_dwordx4 v[56:59], v4, s[4:5] offset:1024
	global_load_dwordx4 v[52:55], v4, s[4:5] offset:2048
	global_load_dwordx4 v[48:51], v4, s[4:5] offset:3072
	v_addc_co_u32_e32 v7, vcc, 0, v1, vcc
	global_load_dwordx4 v[44:47], v[6:7], off
	global_load_dwordx4 v[40:43], v[6:7], off offset:1024
	global_load_dwordx4 v[36:39], v[6:7], off offset:2048
	global_load_dwordx4 v[0:3], v[6:7], off offset:3072
	s_lshl_b64 s[6:7], s[70:71], 12
	s_add_u32 s6, s50, s6
	v_lshlrev_b32_e32 v6, 3, v8
	v_mov_b32_e32 v7, v5
	s_addc_u32 s7, s51, s7
	s_add_i32 s8, s70, s52
	v_lshl_add_u64 v[6:7], s[6:7], 0, v[6:7]
	s_mov_b64 s[6:7], 0x5c00e00
	s_ashr_i32 s53, s52, 31
	s_ashr_i32 s9, s8, 31
	v_lshl_add_u64 v[64:65], s[40:41], 0, v[4:5]
	s_mov_b64 s[4:5], 0x1000
	v_lshl_add_u64 v[74:75], v[6:7], 0, s[6:7]
	s_lshl_b64 s[6:7], s[52:53], 12
	s_lshl_b64 s[8:9], s[8:9], 13
	v_lshl_add_u64 v[66:67], v[64:65], 0, s[4:5]
	s_mov_b64 s[4:5], 0x1400
	s_add_u32 s8, s48, s8
	v_lshl_add_u64 v[68:69], v[64:65], 0, s[4:5]
	s_mov_b64 s[4:5], 0x1800
	s_addc_u32 s9, s49, s9
	v_lshl_add_u64 v[70:71], v[64:65], 0, s[4:5]
	s_mov_b64 s[4:5], 0x1c00
	v_lshl_add_u64 v[4:5], s[8:9], 0, v[4:5]
	v_lshl_add_u64 v[72:73], v[64:65], 0, s[4:5]
	v_lshl_add_u64 v[76:77], v[4:5], 0, s[4:5]
	s_lshl_b64 s[8:9], s[52:53], 13
	v_mov_b32_e32 v78, 0x358637bd
	s_mov_b32 s3, 0xf800000
	v_mov_b32_e32 v79, 0x260
	s_mov_b32 s12, s70
	global_load_dwordx4 v[100:103], v[64:65], off
	global_load_dwordx4 v[104:107], v[64:65], off offset:1024
	global_load_dwordx4 v[108:111], v[64:65], off offset:2048
	global_load_dwordx4 v[112:115], v[64:65], off offset:3072
	global_load_dwordx4 v[116:119], v[66:67], off
	global_load_dwordx4 v[120:123], v[68:69], off
	global_load_dwordx4 v[124:127], v[70:71], off
	global_load_dwordx4 v[128:131], v[72:73], off
	s_branch .LBB0_624
.LBB0_623:
	s_waitcnt vmcnt(8)
.Lp6_body:
	v_pk_mul_f32 v[92:93], v[60:61], v[60:61]
	v_pk_mul_f32 v[94:95], v[56:57], v[56:57]
	v_pk_mul_f32 v[88:89], v[62:63], v[62:63]
	v_pk_mul_f32 v[90:91], v[58:59], v[58:59]
	v_mov_b32_e32 v96, v92
	v_mov_b32_e32 v97, v94
	v_mov_b32_e32 v94, v93
	v_pk_mul_f32 v[84:85], v[54:55], v[54:55]
	v_pk_mul_f32 v[86:87], v[52:53], v[52:53]
	v_pk_add_f32 v[92:93], v[96:97], v[94:95]
	v_mov_b32_e32 v94, v88
	v_mov_b32_e32 v95, v90
	v_mov_b32_e32 v90, v89
	v_pk_add_f32 v[88:89], v[94:95], v[90:91]
	v_pk_mov_b32 v[90:91], v[86:87], v[84:85] op_sel:[1,0]
	v_mov_b32_e32 v87, v85
	v_pk_add_f32 v[84:85], v[90:91], v[86:87]
	v_pk_add_f32 v[88:89], v[92:93], v[88:89]
	v_pk_add_f32 v[84:85], v[84:85], v[84:85] op_sel_hi:[0,1]
	v_mul_f32_e32 v84, v48, v48
	v_pk_fma_f32 v[86:87], v[48:49], v[48:49], v[84:85] op_sel_hi:[1,1,0]
	v_mul_f32_e32 v84, v50, v50
	v_pk_add_f32 v[88:89], v[88:89], v[88:89] op_sel_hi:[0,1]
	v_pk_fma_f32 v[90:91], v[50:51], v[50:51], v[84:85] op_sel_hi:[1,1,0]
	v_mul_f32_e32 v86, v44, v44
	v_mul_f32_e32 v90, v45, v45
	v_mul_f32_e32 v84, v46, v46
	v_mul_f32_e32 v88, v47, v47
	v_pk_mul_f32 v[80:81], v[42:43], v[42:43]
	v_pk_mul_f32 v[82:83], v[40:41], v[40:41]
	v_pk_add_f32 v[86:87], v[86:87], v[90:91]
	v_pk_add_f32 v[84:85], v[84:85], v[88:89]
	v_lshl_add_u64 v[76:77], v[76:77], 0, s[8:9]
	v_pk_add_f32 v[84:85], v[86:87], v[84:85]
	v_pk_mov_b32 v[86:87], v[82:83], v[80:81] op_sel:[1,0]
	v_mov_b32_e32 v83, v81
	v_pk_add_f32 v[80:81], v[86:87], v[82:83]
	v_pk_add_f32 v[84:85], v[84:85], v[84:85] op_sel_hi:[0,1]
	v_pk_add_f32 v[86:87], v[80:81], v[80:81] op_sel_hi:[0,1]
	v_mul_f32_e32 v80, v36, v36
	v_pk_fma_f32 v[88:89], v[36:37], v[36:37], v[80:81] op_sel_hi:[1,1,0]
	v_mul_f32_e32 v80, v38, v38
	v_pk_fma_f32 v[90:91], v[38:39], v[38:39], v[80:81] op_sel_hi:[1,1,0]
	v_mul_f32_e32 v88, v0, v0
	v_mul_f32_e32 v90, v1, v1
	v_mul_f32_e32 v86, v2, v2
	v_mul_f32_e32 v84, v3, v3
	v_pk_add_f32 v[88:89], v[88:89], v[90:91]
	v_pk_add_f32 v[84:85], v[86:87], v[84:85]
	s_nop 0
	v_pk_add_f32 v[84:85], v[88:89], v[84:85]
	s_nop 0
	v_add_f32_e32 v84, v84, v85
	ds_bpermute_b32 v85, v246, v84
	s_waitcnt lgkmcnt(0)
	v_add_f32_e32 v84, v84, v85
	ds_bpermute_b32 v85, v247, v84
	s_waitcnt lgkmcnt(0)
	v_add_f32_e32 v84, v84, v85
	ds_bpermute_b32 v85, v248, v84
	s_waitcnt lgkmcnt(0)
	v_add_f32_e32 v84, v84, v85
	ds_bpermute_b32 v85, v249, v84
	s_waitcnt lgkmcnt(0)
; __device__ __forceinline__ unsigned cvtpk(float lo, float hi) { return pg8::cvt_pk_bf16(lo, hi); }
; __device__ __forceinline__ float rms_rstd(const f32x4 (&v)[8]) {
;     float s = 0.f;
; #pragma unroll
;     for (int j = 0; j < 8; ++j) s += (v[j].x * v[j].x + v[j].y * v[j].y) + (v[j].z * v[j].z + v[j].w * v[j].w);
;     return 1.0f / sqrtf(wave_sum(s) * (1.f / DM) + EPS);
; }
; __device__ __forceinline__ void rms_store_bf16(const f32x4 (&v)[8], const float* g, bf16* orow, int lane) {
;     const float rstd = rms_rstd(v); const f32x4* gr = (const f32x4*)g + lane; v2u* o8 = (v2u*)orow + lane;
; #pragma unroll
;     for (int j = 0; j < 8; ++j) { const f32x4 gg = gr[64 * j]; v2u w; w.x = cvtpk(v[j].x * rstd * gg.x, v[j].y * rstd * gg.y); w.y = cvtpk(v[j].z * rstd * gg.z, v[j].w * rstd * gg.w); o8[64 * j] = w; }
; }
; __global__ void __launch_bounds__(512, 2) fwd_megakernel(Args args) {
;     ...
;     if (IN(6)) { int t_b = threadIdx.x; asm volatile("" : "+v"(t_b)); const int lane = t_b & 63; int m = gw; f32x4 cur[8]; if (m < NTOK) rms_load(args.out + (size_t)m * DM, lane, cur);
;         for (; m < NTOK; m += NGW) { const int mn = m + NGW; f32x4 nxt[8]; if (mn < NTOK) rms_load(args.out + (size_t)mn * DM, lane, nxt);
;             rms_store_bf16(cur, args.in[10], XN + (size_t)m * DM, lane);
; #pragma unroll
;             for (int j = 0; j < 8; ++j) cur[j] = nxt[j]; } }
	v_add_f32_e32 v84, v84, v85
	ds_bpermute_b32 v85, v250, v84
	s_waitcnt lgkmcnt(0)
	v_add_f32_e32 v84, v84, v85
	ds_bpermute_b32 v85, v251, v84
	s_waitcnt lgkmcnt(0)
	v_add_f32_e32 v84, v84, v85
	v_fmamk_f32 v84, v84, 0x3a000000, v78
	v_mul_f32_e32 v85, 0x4f800000, v84
	v_cmp_gt_f32_e32 vcc, s3, v84
	s_nop 1
	v_cndmask_b32_e32 v84, v84, v85, vcc
	v_sqrt_f32_e32 v85, v84
	s_nop 0
	v_add_u32_e32 v86, -1, v85
	v_fma_f32 v87, -v86, v85, v84
	v_cmp_ge_f32_e64 s[4:5], 0, v87
	v_add_u32_e32 v87, 1, v85
	s_nop 0
	v_cndmask_b32_e64 v86, v85, v86, s[4:5]
	v_fma_f32 v85, -v87, v85, v84
	v_cmp_lt_f32_e64 s[4:5], 0, v85
	s_nop 1
	v_cndmask_b32_e64 v85, v86, v87, s[4:5]
	v_mul_f32_e32 v86, 0x37800000, v85
	v_cndmask_b32_e32 v85, v85, v86, vcc
	v_cmp_class_f32_e32 vcc, v84, v79
	s_nop 1
	v_cndmask_b32_e32 v84, v85, v84, vcc
	v_div_scale_f32 v85, s[4:5], v84, v84, 1.0
	v_rcp_f32_e32 v86, v85
	s_nop 0
	v_fma_f32 v87, -v85, v86, 1.0
	v_fmac_f32_e32 v86, v87, v86
	v_div_scale_f32 v87, vcc, 1.0, v84, 1.0
	v_mul_f32_e32 v88, v87, v86
	v_fma_f32 v89, -v85, v88, v87
	v_fmac_f32_e32 v88, v89, v86
	v_fma_f32 v85, -v85, v88, v87
	v_div_fmas_f32 v85, v85, v86, v88
	v_div_fixup_f32 v84, v85, v84, 1.0
	v_pk_mul_f32 v[60:61], v[60:61], v[84:85] op_sel_hi:[1,0]
	v_pk_mul_f32 v[62:63], v[62:63], v[84:85] op_sel_hi:[1,0]
	v_pk_mul_f32 v[60:61], v[100:101], v[60:61]
	v_pk_mul_f32 v[62:63], v[102:103], v[62:63]
	v_cvt_pk_bf16_f32 v60, v60, v61
	v_cvt_pk_bf16_f32 v61, v62, v63
	global_store_dwordx2 v[74:75], v[60:61], off offset:-3584
	v_pk_mul_f32 v[56:57], v[56:57], v[84:85] op_sel_hi:[1,0]
	v_pk_mul_f32 v[58:59], v[58:59], v[84:85] op_sel_hi:[1,0]
	v_pk_mul_f32 v[52:53], v[52:53], v[84:85] op_sel_hi:[1,0]
	v_pk_mul_f32 v[54:55], v[54:55], v[84:85] op_sel_hi:[1,0]
	v_pk_mul_f32 v[48:49], v[48:49], v[84:85] op_sel_hi:[1,0]
	v_pk_mul_f32 v[50:51], v[50:51], v[84:85] op_sel_hi:[1,0]
	v_pk_mul_f32 v[44:45], v[44:45], v[84:85] op_sel_hi:[1,0]
	v_pk_mul_f32 v[46:47], v[46:47], v[84:85] op_sel_hi:[1,0]
	v_pk_mul_f32 v[40:41], v[40:41], v[84:85] op_sel_hi:[1,0]
	v_pk_mul_f32 v[42:43], v[42:43], v[84:85] op_sel_hi:[1,0]
	v_pk_mul_f32 v[36:37], v[36:37], v[84:85] op_sel_hi:[1,0]
	v_pk_mul_f32 v[38:39], v[38:39], v[84:85] op_sel_hi:[1,0]
	v_pk_mul_f32 v[86:87], v[0:1], v[84:85] op_sel_hi:[1,0]
	v_pk_mul_f32 v[84:85], v[2:3], v[84:85] op_sel_hi:[1,0]
	s_andn2_b64 vcc, exec, s[10:11]
	s_waitcnt vmcnt(1)
	v_mov_b32_e32 v0, v4
	v_mov_b32_e32 v1, v5
	v_mov_b32_e32 v2, v6
	v_mov_b32_e32 v3, v7
	v_pk_mul_f32 v[56:57], v[104:105], v[56:57]
	v_pk_mul_f32 v[58:59], v[106:107], v[58:59]
	v_cvt_pk_bf16_f32 v56, v56, v57
	v_cvt_pk_bf16_f32 v57, v58, v59
	global_store_dwordx2 v[74:75], v[56:57], off offset:-3072
	v_mov_b32_e32 v60, v32
	v_mov_b32_e32 v61, v33
	v_mov_b32_e32 v62, v34
	v_mov_b32_e32 v63, v35
	v_pk_mul_f32 v[52:53], v[108:109], v[52:53]
	v_pk_mul_f32 v[54:55], v[110:111], v[54:55]
	v_cvt_pk_bf16_f32 v52, v52, v53
	v_cvt_pk_bf16_f32 v53, v54, v55
	global_store_dwordx2 v[74:75], v[52:53], off offset:-2560
	v_mov_b32_e32 v56, v28
	v_mov_b32_e32 v57, v29
	v_mov_b32_e32 v58, v30
	v_mov_b32_e32 v59, v31
	v_pk_mul_f32 v[48:49], v[48:49], v[112:113]
	v_pk_mul_f32 v[50:51], v[50:51], v[114:115]
	v_cvt_pk_bf16_f32 v48, v48, v49
	v_cvt_pk_bf16_f32 v49, v50, v51
	global_store_dwordx2 v[74:75], v[48:49], off offset:-2048
	v_mov_b32_e32 v52, v24
	v_mov_b32_e32 v53, v25
	v_mov_b32_e32 v54, v26
	v_mov_b32_e32 v55, v27
	v_pk_mul_f32 v[44:45], v[44:45], v[116:117]
	v_pk_mul_f32 v[46:47], v[46:47], v[118:119]
	v_cvt_pk_bf16_f32 v44, v44, v45
	v_cvt_pk_bf16_f32 v45, v46, v47
	global_store_dwordx2 v[74:75], v[44:45], off offset:-1536
	v_mov_b32_e32 v48, v20
	v_mov_b32_e32 v49, v21
	v_mov_b32_e32 v50, v22
	v_mov_b32_e32 v51, v23
	v_pk_mul_f32 v[40:41], v[40:41], v[120:121]
	v_pk_mul_f32 v[42:43], v[42:43], v[122:123]
	v_cvt_pk_bf16_f32 v40, v40, v41
	v_cvt_pk_bf16_f32 v41, v42, v43
	global_store_dwordx2 v[74:75], v[40:41], off offset:-1024
	v_mov_b32_e32 v44, v16
	v_mov_b32_e32 v45, v17
	v_mov_b32_e32 v46, v18
	v_mov_b32_e32 v47, v19
	v_pk_mul_f32 v[36:37], v[36:37], v[124:125]
	v_pk_mul_f32 v[38:39], v[38:39], v[126:127]
	v_cvt_pk_bf16_f32 v36, v36, v37
	v_cvt_pk_bf16_f32 v37, v38, v39
	global_store_dwordx2 v[74:75], v[36:37], off offset:-512
	v_mov_b32_e32 v40, v12
	v_mov_b32_e32 v41, v13
	v_mov_b32_e32 v42, v14
	v_mov_b32_e32 v43, v15
	v_mov_b32_e32 v36, v8
	v_mov_b32_e32 v37, v9
	v_mov_b32_e32 v38, v10
	v_mov_b32_e32 v39, v11
	v_pk_mul_f32 v[80:81], v[86:87], v[128:129]
	v_pk_mul_f32 v[82:83], v[84:85], v[130:131]
	v_cvt_pk_bf16_f32 v80, v80, v81
	v_cvt_pk_bf16_f32 v81, v82, v83
	global_store_dwordx2 v[74:75], v[80:81], off
	v_lshl_add_u64 v[74:75], v[74:75], 0, s[6:7]
	s_cbranch_vccz .LBB0_626

; __global__ void __launch_bounds__(512, 2) fwd_megakernel(Args args) {
;     ...
;     if (IN(6)) { int t_b = threadIdx.x; asm volatile("" : "+v"(t_b)); const int lane = t_b & 63; int m = gw; f32x4 cur[8]; if (m < NTOK) rms_load(args.out + (size_t)m * DM, lane, cur);
;         for (; m < NTOK; m += NGW) { const int mn = m + NGW; f32x4 nxt[8]; if (mn < NTOK) rms_load(args.out + (size_t)mn * DM, lane, nxt);
;             rms_store_bf16(cur, args.in[10], XN + (size_t)m * DM, lane);
; #pragma unroll
;             for (int j = 0; j < 8; ++j) cur[j] = nxt[j]; } }
.Lp6_nonext:
	s_waitcnt vmcnt(0)
	s_branch .Lp6_body
